# attn_dma
# speedup vs baseline: 1.0022x; 1.0022x over previous
; #define LAS __attribute__((address_space(3)))
; __device__ __forceinline__ void attn_passes(const Params& p, LAS unsigned char* lds) {
;     ...
;                     if (n < 3) { DMA_CHUNK(4 * n + 7 + j); if (j == 1) DMA_Q(n + 1); }
;                     else if (has_nxt) { DMA_CHUNK_NXT(3 + j); if (j == 1) DMA_Q_NXT(); }
;                 }
;                 const int k = 4 * n + (w >> 1) + j;
;                 LAS unsigned char* kb = lds + (k & 7) * 16384; LAS unsigned char* vb = kb + 8192;
;                 const int lb = Ls - 128 + 32 * k;
;                 bf16x8 kf[8]; s16x4 t0[8], t1[8];
;                 { const unsigned kbo = (unsigned)(size_t)kb;
;                   const unsigned k0 = kbo + koff[0], k1 = kbo + koff[1], k2 = kbo + koff[2], k3 = kbo + koff[3], k4 = kbo + koff[4], k5 = kbo + koff[5], k6 = kbo + koff[6], k7 = kbo + koff[7];
;                   asm volatile("ds_read_b128 %0, %8\n\tds_read_b128 %1, %9\n\tds_read_b128 %2, %10\n\tds_read_b128 %3, %11\n\tds_read_b128 %4, %12\n\tds_read_b128 %5, %13\n\tds_read_b128 %6, %14\n\tds_read_b128 %7, %15"
;                                : "=&v"(kf[0]), "=&v"(kf[4]), "=&v"(kf[1]), "=&v"(kf[5]), "=&v"(kf[2]), "=&v"(kf[6]), "=&v"(kf[3]), "=&v"(kf[7])
;                                : "v"(k0), "v"(k4), "v"(k1), "v"(k5), "v"(k2), "v"(k6), "v"(k3), "v"(k7) : "memory"); }
;                 const unsigned vbo = (unsigned)(size_t)vb;
;     ...
;                 TR_BATCH(0);
;                 asm volatile("s_waitcnt lgkmcnt(8)" : "+v"(kf[0]), "+v"(kf[1]), "+v"(kf[2]), "+v"(kf[3]), "+v"(kf[4]), "+v"(kf[5]), "+v"(kf[6]), "+v"(kf[7]) :: "memory");
;                 f32x4 s1 = (f32x4){0.f, 0.f, 0.f, 0.f}, s2 = s1;
; #pragma unroll
;                 for (int ks = 0; ks < 4; ++ks) {
;                     s1 = __builtin_amdgcn_mfma_f32_16x16x32_bf16(kf[ks], qf[ks], s1, 0, 0, 0); s2 = __builtin_amdgcn_mfma_f32_16x16x32_bf16(kf[4 + ks], qf[ks], s2, 0, 0, 0); }
;                 TR_BATCH(1);
;     ...
;                 const int rel0 = lq - lb - 8 * g;
;                 const float bias0 = -sd * (float)rel0;
;                 float sv[8];
;                 if (j >= 1 && j <= 3 && lb >= 0) {
; #pragma unroll
;                     for (int jj = 0; jj < 8; ++jj) { const float raw = jj < 4 ? s1[jj & 3] : s2[jj & 3]; sv[jj] = raw * sc2 + (bias0 + sd * (float)jj); }
.LBB0_275:
	s_barrier
	s_add_i32 s12, s93, 0xfffdc000
	s_and_b32 s12, s12, 0x1c000
	s_add_i32 s12, s12, 0
	s_add_i32 s13, s12, 0x2000
	v_add_u32_e32 v48, s12, v135
	v_add_u32_e32 v49, s12, v139
	v_add_u32_e32 v50, s12, v174
	v_add_u32_e32 v51, s12, v176
	v_add_u32_e32 v56, s12, v137
	v_add_u32_e32 v57, s12, v141
	v_add_u32_e32 v58, s12, v175
	v_add_u32_e32 v59, s12, v177
	ds_read_b128 v[52:55], v48
	ds_read_b128 v[80:83], v56
	ds_read_b128 v[64:67], v49
	ds_read_b128 v[84:87], v57
	ds_read_b128 v[72:75], v50
	ds_read_b128 v[216:219], v58
	ds_read_b128 v[76:79], v51
	ds_read_b128 v[220:223], v59
	v_add_u32_e32 v88, s13, v178
	v_add_u32_e32 v89, s13, v179
	v_add_u32_e32 v215, s13, v181
	v_add_u32_e32 v224, s13, v188
	v_add_u32_e32 v225, s13, v182
	v_add_u32_e32 v226, s13, v189
	v_add_u32_e32 v227, s13, v183
	v_add_u32_e32 v228, s13, v190
	ds_read_b64_tr_b16 v[68:69], v88
	ds_read_b64_tr_b16 v[70:71], v89
	ds_read_b64_tr_b16 v[60:61], v215
	ds_read_b64_tr_b16 v[62:63], v224
	ds_read_b64_tr_b16 v[56:57], v225
	ds_read_b64_tr_b16 v[58:59], v226
	ds_read_b64_tr_b16 v[48:49], v227
	ds_read_b64_tr_b16 v[50:51], v228
	v_cndmask_b32_e64 v230, 0, 1, s[10:11]
	v_cmp_ne_u32_e64 s[6:7], 1, v230
	s_andn2_b64 vcc, exec, s[10:11]
	s_mov_b64 s[10:11], -1
	s_cbranch_vccnz .LBB0_277
	v_add_u32_e32 v230, 0xa0, v102
	v_max_i32_e32 v230, 0, v230
	v_min_i32_e32 v230, s88, v230
	v_mov_b32_e32 v231, v91
	v_lshlrev_b64 v[230:231], s87, v[230:231]
	s_add_i32 s10, s91, 0xffff8000
	v_lshl_add_u64 v[230:231], v[230:231], 0, s[22:23]
	s_and_b32 s10, s10, 0x14000
	v_lshlrev_b64 v[230:231], 8, v[230:231]
	s_add_i32 s10, s55, s10
	v_lshl_add_u64 v[232:233], v[104:105], 0, v[230:231]
	s_mov_b32 m0, s10
	v_lshl_add_u64 v[230:231], v[106:107], 0, v[230:231]
	global_load_lds_dwordx4 v[232:233], off
	s_add_i32 m0, s10, 0x2000
	s_mov_b64 s[10:11], 0
	global_load_lds_dwordx4 v[230:231], off
.LBB0_277:
	v_cndmask_b32_e64 v230, 0, 1, s[46:47]
	s_andn2_b64 vcc, exec, s[10:11]
	v_cmp_ne_u32_e64 s[10:11], 1, v230
	s_cbranch_vccnz .LBB0_280
	s_and_b64 vcc, exec, s[10:11]
	s_cbranch_vccnz .LBB0_280
	s_mov_b32 m0, s60
	s_nop 0
	global_load_lds_dwordx4 v[144:145], off
	s_mov_b32 m0, s61
	s_nop 0
	global_load_lds_dwordx4 v[146:147], off
.LBB0_280:
	s_waitcnt lgkmcnt(8)
	v_add_u32_e32 v88, s13, v184
	v_mfma_f32_16x16x32_bf16 v[52:55], v[52:55], v[12:15], 0
	v_add_u32_e32 v89, s13, v191
	v_add_u32_e32 v215, s13, v185
	s_sub_i32 s12, s92, 64
	v_mfma_f32_16x16x32_bf16 v[80:83], v[80:83], v[12:15], 0
	s_cmp_lt_i32 s12, 0
	v_mfma_f32_16x16x32_bf16 v[52:55], v[64:67], v[8:11], v[52:55]
	v_mfma_f32_16x16x32_bf16 v[64:67], v[84:87], v[8:11], v[80:83]
	v_mfma_f32_16x16x32_bf16 v[52:55], v[72:75], v[4:7], v[52:55]
	v_mfma_f32_16x16x32_bf16 v[64:67], v[216:219], v[4:7], v[64:67]
	v_add_u32_e32 v216, s13, v192
	v_add_u32_e32 v217, s13, v186
	v_add_u32_e32 v218, s13, v193
	v_mfma_f32_16x16x32_bf16 v[84:87], v[76:79], v[0:3], v[52:55]
	v_add_u32_e32 v219, s13, v187
	v_mfma_f32_16x16x32_bf16 v[80:83], v[220:223], v[0:3], v[64:67]
	v_add_u32_e32 v220, s13, v194
	ds_read_b64_tr_b16 v[76:77], v88
	ds_read_b64_tr_b16 v[78:79], v89
	ds_read_b64_tr_b16 v[72:73], v215
	ds_read_b64_tr_b16 v[74:75], v216
	ds_read_b64_tr_b16 v[64:65], v217
	ds_read_b64_tr_b16 v[66:67], v218
	ds_read_b64_tr_b16 v[52:53], v219
	ds_read_b64_tr_b16 v[54:55], v220
	s_cbranch_scc1 .LBB0_282
	v_add_u32_e32 v88, 64, v208
	v_cvt_f32_i32_e32 v88, v88
	v_mul_f32_e64 v216, -v111, v88
	v_pk_add_f32 v[88:89], v[110:111], v[216:217] op_sel_hi:[1,0]
	v_pk_add_f32 v[220:221], v[114:115], v[216:217] op_sel_hi:[1,0]
	v_pk_add_f32 v[218:219], v[112:113], v[216:217] op_sel_hi:[1,0]
	v_pk_fma_f32 v[88:89], v[84:85], s[36:37], v[88:89] op_sel_hi:[1,0,1]
	v_pk_fma_f32 v[84:85], v[80:81], s[36:37], v[220:221] op_sel_hi:[1,0,1]
	v_pk_add_f32 v[80:81], v[116:117], v[216:217] op_sel_hi:[1,0]
	v_pk_fma_f32 v[86:87], v[86:87], s[36:37], v[218:219] op_sel_hi:[1,0,1]
	v_pk_fma_f32 v[80:81], v[82:83], s[36:37], v[80:81] op_sel_hi:[1,0,1]
	s_branch .LBB0_283

; #define LAS __attribute__((address_space(3)))
; __device__ __forceinline__ void attn_passes(const Params& p, LAS unsigned char* lds) {
;     ...
;                     if (n < 3) { DMA_CHUNK(4 * n + 7 + j); if (j == 1) DMA_Q(n + 1); }
;                     else if (has_nxt) { DMA_CHUNK_NXT(3 + j); if (j == 1) DMA_Q_NXT(); }
;                 }
;                 const int k = 4 * n + (w >> 1) + j;
;                 LAS unsigned char* kb = lds + (k & 7) * 16384; LAS unsigned char* vb = kb + 8192;
;                 const int lb = Ls - 128 + 32 * k;
;                 bf16x8 kf[8]; s16x4 t0[8], t1[8];
;                 { const unsigned kbo = (unsigned)(size_t)kb;
;                   const unsigned k0 = kbo + koff[0], k1 = kbo + koff[1], k2 = kbo + koff[2], k3 = kbo + koff[3], k4 = kbo + koff[4], k5 = kbo + koff[5], k6 = kbo + koff[6], k7 = kbo + koff[7];
;                   asm volatile("ds_read_b128 %0, %8\n\tds_read_b128 %1, %9\n\tds_read_b128 %2, %10\n\tds_read_b128 %3, %11\n\tds_read_b128 %4, %12\n\tds_read_b128 %5, %13\n\tds_read_b128 %6, %14\n\tds_read_b128 %7, %15"
;                                : "=&v"(kf[0]), "=&v"(kf[4]), "=&v"(kf[1]), "=&v"(kf[5]), "=&v"(kf[2]), "=&v"(kf[6]), "=&v"(kf[3]), "=&v"(kf[7])
;                                : "v"(k0), "v"(k4), "v"(k1), "v"(k5), "v"(k2), "v"(k6), "v"(k3), "v"(k7) : "memory"); }
;                 const unsigned vbo = (unsigned)(size_t)vb;
;     ...
;                 TR_BATCH(0);
;                 asm volatile("s_waitcnt lgkmcnt(8)" : "+v"(kf[0]), "+v"(kf[1]), "+v"(kf[2]), "+v"(kf[3]), "+v"(kf[4]), "+v"(kf[5]), "+v"(kf[6]), "+v"(kf[7]) :: "memory");
;                 f32x4 s1 = (f32x4){0.f, 0.f, 0.f, 0.f}, s2 = s1;
; #pragma unroll
;                 for (int ks = 0; ks < 4; ++ks) {
;                     s1 = __builtin_amdgcn_mfma_f32_16x16x32_bf16(kf[ks], qf[ks], s1, 0, 0, 0); s2 = __builtin_amdgcn_mfma_f32_16x16x32_bf16(kf[4 + ks], qf[ks], s2, 0, 0, 0); }
;                 TR_BATCH(1);
;     ...
;                 const int rel0 = lq - lb - 8 * g;
;                 const float bias0 = -sd * (float)rel0;
;                 float sv[8];
;                 if (j >= 1 && j <= 3 && lb >= 0) {
; #pragma unroll
;                     for (int jj = 0; jj < 8; ++jj) { const float raw = jj < 4 ? s1[jj & 3] : s2[jj & 3]; sv[jj] = raw * sc2 + (bias0 + sd * (float)jj); }
.LBB0_290:
	s_barrier
	s_add_i32 s52, s93, 0xfffe0000
	s_and_b32 s52, s52, 0x1c000
	s_add_i32 s52, s52, 0
	s_add_i32 s53, s52, 0x2000
	v_add_u32_e32 v48, s52, v135
	v_add_u32_e32 v49, s52, v139
	v_add_u32_e32 v50, s52, v174
	v_add_u32_e32 v51, s52, v176
	v_add_u32_e32 v52, s52, v137
	v_add_u32_e32 v53, s52, v141
	v_add_u32_e32 v54, s52, v175
	v_add_u32_e32 v55, s52, v177
	ds_read_b128 v[56:59], v48
	ds_read_b128 v[80:83], v52
	ds_read_b128 v[64:67], v49
	ds_read_b128 v[84:87], v53
	ds_read_b128 v[72:75], v50
	ds_read_b128 v[216:219], v54
	ds_read_b128 v[76:79], v51
	ds_read_b128 v[220:223], v55
	v_add_u32_e32 v88, s53, v178
	v_add_u32_e32 v89, s53, v179
	v_add_u32_e32 v215, s53, v181
	v_add_u32_e32 v224, s53, v188
	v_add_u32_e32 v225, s53, v182
	v_add_u32_e32 v226, s53, v189
	v_add_u32_e32 v227, s53, v183
	v_add_u32_e32 v228, s53, v190
	ds_read_b64_tr_b16 v[68:69], v88
	ds_read_b64_tr_b16 v[70:71], v89
	ds_read_b64_tr_b16 v[60:61], v215
	ds_read_b64_tr_b16 v[62:63], v224
	ds_read_b64_tr_b16 v[52:53], v225
	ds_read_b64_tr_b16 v[54:55], v226
	ds_read_b64_tr_b16 v[48:49], v227
	ds_read_b64_tr_b16 v[50:51], v228
	s_and_b64 vcc, exec, s[6:7]
	s_mov_b64 s[98:99], -1
	s_cbranch_vccnz .LBB0_292
	v_add_u32_e32 v230, 0xc0, v102
	v_max_i32_e32 v230, 0, v230
	v_min_i32_e32 v230, s88, v230
	v_mov_b32_e32 v231, v91
	v_lshlrev_b64 v[230:231], s87, v[230:231]
	s_add_i32 s98, s91, 0xffffc000
	v_lshl_add_u64 v[230:231], v[230:231], 0, s[22:23]
	s_and_b32 s98, s98, 0x18000
	v_lshlrev_b64 v[230:231], 8, v[230:231]
	s_add_i32 s98, s55, s98
	v_lshl_add_u64 v[232:233], v[104:105], 0, v[230:231]
	s_mov_b32 m0, s98
	v_lshl_add_u64 v[230:231], v[106:107], 0, v[230:231]
	global_load_lds_dwordx4 v[232:233], off
	s_add_i32 m0, s98, 0x2000
	s_mov_b64 s[98:99], 0
	global_load_lds_dwordx4 v[230:231], off
.LBB0_292:
	s_andn2_b64 vcc, exec, s[98:99]
	s_cbranch_vccnz .LBB0_295
	s_and_b64 vcc, exec, s[10:11]
	s_cbranch_vccnz .LBB0_295
	s_mov_b32 m0, s62
	s_nop 0
	global_load_lds_dwordx4 v[148:149], off
	s_mov_b32 m0, s63
	s_nop 0
	global_load_lds_dwordx4 v[150:151], off
.LBB0_295:
	s_waitcnt lgkmcnt(8)
	v_add_u32_e32 v88, s53, v184
	v_mfma_f32_16x16x32_bf16 v[56:59], v[56:59], v[12:15], 0
	v_add_u32_e32 v89, s53, v191
	v_add_u32_e32 v215, s53, v185
	s_sub_i32 s52, s92, 32
	v_mfma_f32_16x16x32_bf16 v[80:83], v[80:83], v[12:15], 0
	s_cmp_lt_i32 s52, 0
	v_mfma_f32_16x16x32_bf16 v[56:59], v[64:67], v[8:11], v[56:59]
	v_mfma_f32_16x16x32_bf16 v[64:67], v[84:87], v[8:11], v[80:83]
	v_mfma_f32_16x16x32_bf16 v[56:59], v[72:75], v[4:7], v[56:59]
	v_mfma_f32_16x16x32_bf16 v[64:67], v[216:219], v[4:7], v[64:67]
	v_add_u32_e32 v216, s53, v192
	v_add_u32_e32 v217, s53, v186
	v_add_u32_e32 v218, s53, v193
	v_mfma_f32_16x16x32_bf16 v[84:87], v[76:79], v[0:3], v[56:59]
	v_add_u32_e32 v219, s53, v187
	v_mfma_f32_16x16x32_bf16 v[80:83], v[220:223], v[0:3], v[64:67]
	v_add_u32_e32 v220, s53, v194
	ds_read_b64_tr_b16 v[76:77], v88
	ds_read_b64_tr_b16 v[78:79], v89
	ds_read_b64_tr_b16 v[72:73], v215
	ds_read_b64_tr_b16 v[74:75], v216
	ds_read_b64_tr_b16 v[64:65], v217
	ds_read_b64_tr_b16 v[66:67], v218
	ds_read_b64_tr_b16 v[56:57], v219
	ds_read_b64_tr_b16 v[58:59], v220
	s_cbranch_scc1 .LBB0_297
	v_add_u32_e32 v88, 32, v208
	v_cvt_f32_i32_e32 v88, v88
	v_mul_f32_e64 v216, -v111, v88
	v_pk_add_f32 v[88:89], v[110:111], v[216:217] op_sel_hi:[1,0]
	v_pk_add_f32 v[220:221], v[114:115], v[216:217] op_sel_hi:[1,0]
	v_pk_add_f32 v[218:219], v[112:113], v[216:217] op_sel_hi:[1,0]
	v_pk_fma_f32 v[88:89], v[84:85], s[36:37], v[88:89] op_sel_hi:[1,0,1]
	v_pk_fma_f32 v[84:85], v[80:81], s[36:37], v[220:221] op_sel_hi:[1,0,1]
	v_pk_add_f32 v[80:81], v[116:117], v[216:217] op_sel_hi:[1,0]
	v_pk_fma_f32 v[86:87], v[86:87], s[36:37], v[218:219] op_sel_hi:[1,0,1]
	v_pk_fma_f32 v[80:81], v[82:83], s[36:37], v[80:81] op_sel_hi:[1,0,1]
	s_branch .LBB0_298

; __device__ __forceinline__ void attn_passes(const Params& p, LAS unsigned char* lds) {
;     ...
;             for (int j = 0; j < 5; ++j) {
;                 if (j >= 1) {
;                     if (n < 3) { DMA_CHUNK(4 * n + 7 + j); if (j == 1) DMA_Q(n + 1); }
;                     else if (has_nxt) { DMA_CHUNK_NXT(3 + j); if (j == 1) DMA_Q_NXT(); }
;                 }
;                 const int k = 4 * n + (w >> 1) + j;
;                 LAS unsigned char* kb = lds + (k & 7) * 16384; LAS unsigned char* vb = kb + 8192;
;                 const int lb = Ls - 128 + 32 * k;
;                 bf16x8 kf[8]; s16x4 t0[8], t1[8];
;                 { const unsigned kbo = (unsigned)(size_t)kb;
;                   const unsigned k0 = kbo + koff[0], k1 = kbo + koff[1], k2 = kbo + koff[2], k3 = kbo + koff[3], k4 = kbo + koff[4], k5 = kbo + koff[5], k6 = kbo + koff[6], k7 = kbo + koff[7];
;                   asm volatile("ds_read_b128 %0, %8\n\tds_read_b128 %1, %9\n\tds_read_b128 %2, %10\n\tds_read_b128 %3, %11\n\tds_read_b128 %4, %12\n\tds_read_b128 %5, %13\n\tds_read_b128 %6, %14\n\tds_read_b128 %7, %15"
;                                : "=&v"(kf[0]), "=&v"(kf[4]), "=&v"(kf[1]), "=&v"(kf[5]), "=&v"(kf[2]), "=&v"(kf[6]), "=&v"(kf[3]), "=&v"(kf[7])
;                                : "v"(k0), "v"(k4), "v"(k1), "v"(k5), "v"(k2), "v"(k6), "v"(k3), "v"(k7) : "memory"); }
;                 const unsigned vbo = (unsigned)(size_t)vb;
;     ...
;                 TR_BATCH(0);
;                 asm volatile("s_waitcnt lgkmcnt(8)" : "+v"(kf[0]), "+v"(kf[1]), "+v"(kf[2]), "+v"(kf[3]), "+v"(kf[4]), "+v"(kf[5]), "+v"(kf[6]), "+v"(kf[7]) :: "memory");
;                 f32x4 s1 = (f32x4){0.f, 0.f, 0.f, 0.f}, s2 = s1;
; #pragma unroll
;                 for (int ks = 0; ks < 4; ++ks) {
;                     s1 = __builtin_amdgcn_mfma_f32_16x16x32_bf16(kf[ks], qf[ks], s1, 0, 0, 0); s2 = __builtin_amdgcn_mfma_f32_16x16x32_bf16(kf[4 + ks], qf[ks], s2, 0, 0, 0); }
;                 TR_BATCH(1);
;     ...
;                 const int rel0 = lq - lb - 8 * g;
;                 const float bias0 = -sd * (float)rel0;
;                 float sv[8];
;                 if (j >= 1 && j <= 3 && lb >= 0) {
; #pragma unroll
;                     for (int jj = 0; jj < 8; ++jj) { const float raw = jj < 4 ? s1[jj & 3] : s2[jj & 3]; sv[jj] = raw * sc2 + (bias0 + sd * (float)jj); }
;                 } else {
.LBB0_305:
	s_barrier
	s_mov_b64 s[100:101], s[10:11]
	v_add_u32_e32 v230, 0xe0, v102
	s_add_i32 s93, s93, 0xfffe4000
	s_and_b32 s8, s93, 0x1c000
	s_add_i32 s8, s8, 0
	s_add_i32 s10, s8, 0x2000
	v_add_u32_e32 v48, s8, v135
	v_add_u32_e32 v49, s8, v139
	v_add_u32_e32 v50, s8, v174
	v_add_u32_e32 v51, s8, v176
	v_add_u32_e32 v52, s8, v137
	v_add_u32_e32 v53, s8, v141
	v_add_u32_e32 v54, s8, v175
	v_add_u32_e32 v55, s8, v177
	ds_read_b128 v[64:67], v48
	ds_read_b128 v[210:213], v52
	ds_read_b128 v[68:71], v49
	ds_read_b128 v[214:217], v53
	ds_read_b128 v[72:75], v50
	ds_read_b128 v[218:221], v54
	ds_read_b128 v[76:79], v51
	ds_read_b128 v[222:225], v55
	v_add_u32_e32 v89, s10, v178
	v_add_u32_e32 v102, s10, v179
	v_add_u32_e32 v159, s10, v181
	v_add_u32_e32 v162, s10, v188
	v_add_u32_e32 v163, s10, v182
	v_add_u32_e32 v209, s10, v189
	v_add_u32_e32 v226, s10, v183
	v_add_u32_e32 v227, s10, v190
	ds_read_b64_tr_b16 v[60:61], v89
	ds_read_b64_tr_b16 v[62:63], v102
	ds_read_b64_tr_b16 v[56:57], v159
	ds_read_b64_tr_b16 v[58:59], v162
	ds_read_b64_tr_b16 v[52:53], v163
	ds_read_b64_tr_b16 v[54:55], v209
	ds_read_b64_tr_b16 v[48:49], v226
	ds_read_b64_tr_b16 v[50:51], v227
	s_and_b64 vcc, exec, s[6:7]
	s_mov_b64 s[98:99], -1
	s_cbranch_vccnz .LBB0_307
	v_max_i32_e32 v230, 0, v230
	v_min_i32_e32 v230, s88, v230
	v_mov_b32_e32 v231, v91
	v_lshlrev_b64 v[230:231], s87, v[230:231]
	v_lshl_add_u64 v[230:231], v[230:231], 0, s[22:23]
	s_and_b32 s98, s91, 0x1c000
	v_lshlrev_b64 v[230:231], 8, v[230:231]
	s_add_i32 s98, s55, s98
	v_lshl_add_u64 v[232:233], v[104:105], 0, v[230:231]
	s_mov_b32 m0, s98
	v_lshl_add_u64 v[230:231], v[106:107], 0, v[230:231]
	global_load_lds_dwordx4 v[232:233], off
	s_add_i32 m0, s98, 0x2000
	s_mov_b64 s[98:99], 0
	global_load_lds_dwordx4 v[230:231], off
.LBB0_307:
	s_andn2_b64 vcc, exec, s[98:99]
	s_cbranch_vccnz .LBB0_310
	s_and_b64 vcc, exec, s[100:101]
	s_cbranch_vccnz .LBB0_310
	s_mov_b32 m0, s64
	s_nop 0
	global_load_lds_dwordx4 v[152:153], off
	s_mov_b32 m0, s65
	s_nop 0
	global_load_lds_dwordx4 v[154:155], off
.LBB0_310:
	s_waitcnt lgkmcnt(8)
	v_cvt_f32_i32_e32 v102, v208
	v_mfma_f32_16x16x32_bf16 v[64:67], v[64:67], v[12:15], 0
	s_cmp_gt_i32 s92, -1
	s_cselect_b64 s[8:9], -1, 0
	v_cmp_gt_u32_e32 vcc, s84, v208
	v_mfma_f32_16x16x32_bf16 v[12:15], v[210:213], v[12:15], 0
	s_and_b64 vcc, s[8:9], vcc
	v_mfma_f32_16x16x32_bf16 v[64:67], v[68:71], v[8:11], v[64:67]
	v_mfma_f32_16x16x32_bf16 v[8:11], v[214:217], v[8:11], v[12:15]
	v_mfma_f32_16x16x32_bf16 v[12:15], v[72:75], v[4:7], v[64:67]
	v_add_u32_e32 v73, s10, v184
	v_add_u32_e32 v74, s10, v191
	v_add_u32_e32 v75, s10, v185
	s_nop 2
	v_add_f32_e32 v64, 0, v83
	v_add_f32_e32 v64, v88, v64
	v_add_f32_e32 v64, v86, v64
	v_mfma_f32_16x16x32_bf16 v[4:7], v[218:221], v[4:7], v[8:11]
	s_nop 2
	v_add_f32_e32 v8, v87, v64
	v_add_f32_e32 v8, v84, v8
	v_add_f32_e32 v64, v85, v8
	v_mfma_f32_16x16x32_bf16 v[8:11], v[76:79], v[0:3], v[12:15]
	v_add_u32_e32 v76, s10, v192
	v_add_u32_e32 v77, s10, v186
	v_mfma_f32_16x16x32_bf16 v[0:3], v[222:225], v[0:3], v[4:7]
	v_add_f32_e32 v12, v80, v64
	s_nop 3
	v_mov_b32_e32 v159, v8
	v_add_f32_e32 v12, v81, v12
	v_pk_mul_f32 v[4:5], v[158:159], v[102:103]
	v_add_f32_e32 v64, v82, v12
	v_add_f32_e32 v6, v110, v4
	v_add_f32_e32 v5, v6, v5
	v_cndmask_b32_e32 v65, v203, v5, vcc
	v_add_u32_e32 v5, -1, v208
	v_cmp_gt_u32_e32 vcc, s84, v5
	v_add_f32_e32 v5, v111, v4
	v_fmac_f32_e32 v5, 0x3e0293ee, v9
	s_and_b64 vcc, s[8:9], vcc
	v_cndmask_b32_e32 v66, v203, v5, vcc
	v_add_u32_e32 v5, -2, v208
	v_cmp_gt_u32_e32 vcc, s84, v5
	v_add_f32_e32 v5, v112, v4
	v_fmac_f32_e32 v5, 0x3e0293ee, v10
	s_and_b64 vcc, s[8:9], vcc
	v_cndmask_b32_e32 v67, v203, v5, vcc
	v_add_u32_e32 v5, -3, v208
	v_cmp_gt_u32_e32 vcc, s84, v5
	v_add_f32_e32 v5, v113, v4
	v_fmac_f32_e32 v5, 0x3e0293ee, v11
	s_and_b64 vcc, s[8:9], vcc
	v_cndmask_b32_e32 v68, v203, v5, vcc
	v_add_u32_e32 v5, -4, v208
	v_cmp_gt_u32_e32 vcc, s84, v5
	v_add_f32_e32 v5, v114, v4
	v_fmac_f32_e32 v5, 0x3e0293ee, v0
	s_and_b64 vcc, s[8:9], vcc
	v_add_u32_e32 v0, -5, v208
	v_cndmask_b32_e32 v69, v203, v5, vcc
	v_cmp_gt_u32_e32 vcc, s84, v0
	v_add_f32_e32 v0, v115, v4
	v_fmac_f32_e32 v0, 0x3e0293ee, v1
	s_and_b64 vcc, s[8:9], vcc
	v_cndmask_b32_e32 v70, v203, v0, vcc
	v_add_u32_e32 v0, -6, v208
	v_cmp_gt_u32_e32 vcc, s84, v0
	v_add_f32_e32 v0, v116, v4
	v_fmac_f32_e32 v0, 0x3e0293ee, v2
	s_and_b64 vcc, s[8:9], vcc
	v_cndmask_b32_e32 v71, v203, v0, vcc
	v_add_u32_e32 v0, -7, v208
	v_cmp_gt_u32_e32 vcc, s84, v0
	v_add_f32_e32 v0, v117, v4
	v_fmac_f32_e32 v0, 0x3e0293ee, v3
	s_and_b64 vcc, s[8:9], vcc
	v_cndmask_b32_e32 v72, v203, v0, vcc
	v_max_f32_e32 v2, v71, v72
	v_max_f32_e32 v0, v65, v66
	v_max_f32_e32 v1, v67, v68
	v_max3_f32 v2, v69, v70, v2
	v_max3_f32 v0, v0, v1, v2
	v_mov_b32_e32 v1, v0
	v_add_u32_e32 v80, s10, v193
	v_add_u32_e32 v81, s10, v187
	v_add_u32_e32 v82, s10, v194
	v_permlane16_swap_b32_e32 v0, v1
	v_max_f32_e32 v78, v0, v1
	v_mov_b32_e32 v79, v78
	ds_read_b64_tr_b16 v[12:13], v73
	ds_read_b64_tr_b16 v[14:15], v74
	ds_read_b64_tr_b16 v[8:9], v75
	ds_read_b64_tr_b16 v[10:11], v76
	ds_read_b64_tr_b16 v[4:5], v77
	ds_read_b64_tr_b16 v[6:7], v80
	ds_read_b64_tr_b16 v[0:1], v81
	ds_read_b64_tr_b16 v[2:3], v82
	v_add_f32_e32 v74, 0x41000000, v160
	v_mov_b32_e32 v73, v78
	s_nop 1
	v_permlane32_swap_b32_e32 v73, v79
	v_max_f32_e32 v73, v73, v79
	v_cmp_gt_f32_e32 vcc, v73, v74
	s_cbranch_vccz .LBB0_312
	v_max_f32_e32 v73, v73, v73
	v_max_f32_e32 v74, v160, v160
	v_max_f32_e32 v73, v74, v73
	v_sub_f32_e32 v74, v160, v73
	v_exp_f32_e32 v74, v74
	v_mov_b32_e32 v160, v73
	v_pk_mul_f32 v[46:47], v[46:47], v[74:75] op_sel_hi:[1,0]
	v_pk_mul_f32 v[44:45], v[44:45], v[74:75] op_sel_hi:[1,0]
	v_pk_mul_f32 v[42:43], v[42:43], v[74:75] op_sel_hi:[1,0]
	v_pk_mul_f32 v[40:41], v[40:41], v[74:75] op_sel_hi:[1,0]
	v_pk_mul_f32 v[38:39], v[38:39], v[74:75] op_sel_hi:[1,0]
	v_pk_mul_f32 v[36:37], v[36:37], v[74:75] op_sel_hi:[1,0]
	v_pk_mul_f32 v[34:35], v[34:35], v[74:75] op_sel_hi:[1,0]
	v_pk_mul_f32 v[32:33], v[32:33], v[74:75] op_sel_hi:[1,0]
	v_pk_mul_f32 v[30:31], v[30:31], v[74:75] op_sel_hi:[1,0]
	v_pk_mul_f32 v[28:29], v[28:29], v[74:75] op_sel_hi:[1,0]
	v_pk_mul_f32 v[26:27], v[26:27], v[74:75] op_sel_hi:[1,0]
	v_pk_mul_f32 v[24:25], v[24:25], v[74:75] op_sel_hi:[1,0]
	v_pk_mul_f32 v[22:23], v[22:23], v[74:75] op_sel_hi:[1,0]
	v_pk_mul_f32 v[20:21], v[20:21], v[74:75] op_sel_hi:[1,0]
	v_pk_mul_f32 v[18:19], v[18:19], v[74:75] op_sel_hi:[1,0]
	v_pk_mul_f32 v[16:17], v[16:17], v[74:75] op_sel_hi:[1,0]
	v_mul_f32_e32 v64, v64, v74
